# stack: VAR2 V prefetch + VAR1 K/bias/V prefetch + lazy softmax rescale (raise running max only when exceeded by >8 log2 units)
# speedup vs baseline: 1.0024x; 1.0003x over previous
; #define LAS __attribute__((address_space(3)))
; __device__ __forceinline__ float pair_max(float v) { float a, b; lohi(v, a, b); return fmaxf(a, b); }
; __device__ __forceinline__ void softmax_pv(f32x16& p0, f32x16& p1, float& m, float& l, f32x16 (&o)[2], LAS float* wsf, const LAS unsigned char* vp, int r32, int hi) {
;     float rm = fmaxf(p0[0], p1[0]);
; #pragma unroll
;     for (int r = 1; r < 16; ++r) rm = fmaxf(rm, fmaxf(p0[r], p1[r]));
;     rm = pair_max(rm);
;     if (__all(rm - m < -151.0f)) return;
;     const float mnew = fmaxf(m, rm), alpha = __builtin_amdgcn_exp2f(m - mnew);
;     m = mnew;
;     float s = 0.f;
; #pragma unroll
;     for (int r = 0; r < 16; ++r) { p0[r] = __builtin_amdgcn_exp2f(p0[r] - mnew); p1[r] = __builtin_amdgcn_exp2f(p1[r] - mnew); s += p0[r] + p1[r]; }
;     l = l * alpha + s;
;     if (__any(alpha != 1.0f)) {
;         if (hi == 0) wsf[r32] = alpha;
; #pragma unroll
;         for (int r = 0; r < 16; ++r) { const float f = wsf[(r & 3) + 8 * (r >> 2) + 4 * hi]; o[0][r] *= f; o[1][r] *= f; }
; template <int VAR>
; __device__ __forceinline__ void attn_unit(LAS unsigned char* lds, const AttnArgs& A, int b, int h, int qb, const int tid) {
;     ...
;                 for (int mp = 0; mp < 2; ++mp) {
;                     f32x16 p0, p1;
; #pragma unroll
;                     for (int r = 0; r < 16; ++r) { p0[r] = 0.f; p1[r] = 0.f; }
;                     __builtin_amdgcn_s_setprio(1);
; #pragma unroll
;                     for (int dd = 0; dd < 2; ++dd) {
;                         const int d0 = 2 * mp + dd;
;                         const bf16x8 b0 = *(const LAS bf16x8*)(kb + d0 * 2048), b1 = *(const LAS bf16x8*)(kb + d0 * 2048 + 512);
;                         p0 = __builtin_amdgcn_mfma_f32_32x32x16_bf16(b0, qr[d0], p0, 0, 0, 0);
;                         p1 = __builtin_amdgcn_mfma_f32_32x32x16_bf16(b1, qr[d0], p1, 0, 0, 0);
;                     }
;                     __builtin_amdgcn_s_setprio(0);
; #pragma unroll
;                     for (int r = 0; r < 16; ++r) {
;                         const float c0 = (float)((r & 3) + 8 * (r >> 2));
;                         p0[r] = __builtin_fmaf(-slope2, __builtin_fabsf(tb - c0), p0[r]);
;                         p1[r] = __builtin_fmaf(-slope2, __builtin_fabsf(tb - (c0 + 32.0f)), p1[r]);
;                     }
.LBB0_453:
	s_add_i32 s38, s84, 2
	s_and_b32 s71, s70, 1
	s_cmp_gt_i32 s38, s81
	s_cselect_b64 s[38:39], -1, 0
	s_or_b64 s[38:39], s[38:39], s[12:13]
	s_and_b64 vcc, exec, s[38:39]
	s_cbranch_vccnz .LBB0_460
	v_add_u32_e32 v66, v140, v141
	v_cvt_f32_i32_e32 v134, v66
	s_lshl_b32 s50, s71, 13
	v_add_u32_e32 v145, s50, v136
	s_setprio 1
	ds_read_b128 v[66:69], v145
	ds_read_b128 v[82:85], v145 offset:512
	ds_read_b128 v[146:149], v145 offset:2048
	s_waitcnt lgkmcnt(2)
	v_mfma_f32_32x32x16_bf16 v[66:81], v[66:69], v[98:101], 0
	s_waitcnt lgkmcnt(0)
	v_mfma_f32_32x32x16_bf16 v[66:81], v[146:149], v[102:105], v[66:81]
	ds_read_b128 v[146:149], v145 offset:2560
	v_mfma_f32_32x32x16_bf16 v[82:97], v[82:85], v[98:101], 0
	s_waitcnt lgkmcnt(0)
	v_mfma_f32_32x32x16_bf16 v[82:97], v[146:149], v[102:105], v[82:97]
	v_add_u32_e32 v253, s50, v137
	ds_read_b64_tr_b16 v[222:223], v253 offset:16384
	ds_read_b64_tr_b16 v[224:225], v253 offset:16896
	ds_read_b64_tr_b16 v[226:227], v253 offset:17408
	ds_read_b64_tr_b16 v[228:229], v253 offset:17920
	ds_read_b64_tr_b16 v[230:231], v253 offset:18432
	ds_read_b64_tr_b16 v[232:233], v253 offset:18944
	ds_read_b64_tr_b16 v[234:235], v253 offset:19456
	ds_read_b64_tr_b16 v[236:237], v253 offset:19968
	ds_read_b64_tr_b16 v[238:239], v253 offset:20480
	ds_read_b64_tr_b16 v[240:241], v253 offset:20992
	ds_read_b64_tr_b16 v[242:243], v253 offset:21504
	ds_read_b64_tr_b16 v[244:245], v253 offset:22016
	ds_read_b64_tr_b16 v[246:247], v253 offset:22528
	ds_read_b64_tr_b16 v[248:249], v253 offset:23040
	ds_read_b64_tr_b16 v[250:251], v253 offset:23552
	ds_read_b64_tr_b16 v[252:253], v253 offset:24064
	s_setprio 0
	v_add_f32_e32 v147, -1.0, v134
	v_add_f32_e32 v148, 0xc2040000, v134
	v_add_f32_e32 v146, 0xc2000000, v134
	s_nop 3
	v_fma_f32 v213, v138, |v147|, v67
	s_nop 2
	v_fma_f32 v214, v138, |v148|, v83
	v_add_f32_e32 v149, -2.0, v134
	v_add_f32_e32 v150, 0xc2080000, v134
	v_add_f32_e32 v151, 0xc0400000, v134
	v_add_f32_e32 v152, 0xc20c0000, v134
	v_add_f32_e32 v173, 0xc1800000, v134
	v_add_f32_e32 v182, 0xc1980000, v134
	v_fma_f32 v215, v138, |v134|, v66
	v_fma_f32 v216, v138, |v146|, v82
	v_fma_f32 v211, v138, |v149|, v68
	v_fma_f32 v212, v138, |v150|, v84
	v_fma_f32 v209, v138, |v151|, v69
	v_fma_f32 v210, v138, |v152|, v85
	v_add_f32_e32 v153, 0xc1000000, v134
	v_add_f32_e32 v166, 0xc2200000, v134
	v_add_f32_e32 v167, 0xc1100000, v134
	v_add_f32_e32 v168, 0xc2240000, v134
	v_add_f32_e32 v169, 0xc1200000, v134
	v_fma_f32 v85, v138, |v173|, v74
	v_fma_f32 v74, v138, |v182|, v77
	v_add_f32_e32 v184, 0xc1c00000, v134
	v_add_f32_e32 v186, 0xc1c80000, v134
	v_max_f32_e32 v77, v213, v214
	v_fma_f32 v207, v138, |v153|, v70
	v_fma_f32 v208, v138, |v166|, v86
	v_fma_f32 v205, v138, |v167|, v71
	v_fma_f32 v206, v138, |v168|, v87
	v_fma_f32 v192, v138, |v169|, v72
	v_add_f32_e32 v170, 0xc2280000, v134
	v_add_f32_e32 v171, 0xc1300000, v134
	v_add_f32_e32 v172, 0xc22c0000, v134
	v_fma_f32 v72, v138, |v184|, v78
	v_fma_f32 v70, v138, |v186|, v79
	v_max3_f32 v77, v215, v216, v77
	v_max_f32_e32 v78, v211, v212
	v_max_f32_e32 v79, v209, v210
	v_fma_f32 v193, v138, |v170|, v88
	v_fma_f32 v87, v138, |v171|, v73
	v_fma_f32 v88, v138, |v172|, v89
	v_add_f32_e32 v177, 0xc2400000, v134
	v_add_f32_e32 v178, 0xc1880000, v134
	v_add_f32_e32 v179, 0xc2440000, v134
	v_max3_f32 v77, v77, v78, v79
	v_max_f32_e32 v78, v207, v208
	v_max_f32_e32 v79, v205, v206
	v_fma_f32 v86, v138, |v177|, v90
	v_fma_f32 v83, v138, |v178|, v75
	v_fma_f32 v84, v138, |v179|, v91
	v_add_f32_e32 v180, 0xc1900000, v134
	v_add_f32_e32 v181, 0xc2480000, v134
	v_add_f32_e32 v183, 0xc24c0000, v134
	v_max3_f32 v77, v77, v78, v79
	v_max_f32_e32 v78, v192, v193
	v_max_f32_e32 v79, v87, v88
	v_fma_f32 v76, v138, |v180|, v76
	v_fma_f32 v82, v138, |v181|, v92
	v_fma_f32 v75, v138, |v183|, v93
	v_add_f32_e32 v185, 0xc2600000, v134
	v_add_f32_e32 v187, 0xc2640000, v134
	v_max3_f32 v77, v77, v78, v79
	v_max_f32_e32 v78, v85, v86
	v_max_f32_e32 v79, v83, v84
	v_fma_f32 v73, v138, |v185|, v94
	v_fma_f32 v71, v138, |v187|, v95
	v_add_f32_e32 v188, 0xc1d00000, v134
	v_add_f32_e32 v189, 0xc2680000, v134
	v_add_f32_e32 v190, 0xc1d80000, v134
	v_add_f32_e32 v191, 0xc26c0000, v134
	v_max3_f32 v77, v77, v78, v79
	v_max_f32_e32 v78, v76, v82
	v_max_f32_e32 v79, v74, v75
	v_fma_f32 v68, v138, |v188|, v80
	v_fma_f32 v69, v138, |v189|, v96
	v_fma_f32 v66, v138, |v190|, v81
	v_fma_f32 v67, v138, |v191|, v97
	v_max3_f32 v77, v77, v78, v79
	v_max_f32_e32 v78, v72, v73
	v_max_f32_e32 v79, v70, v71
	v_max3_f32 v77, v77, v78, v79
	v_max_f32_e32 v78, v68, v69
	v_max_f32_e32 v79, v66, v67
	v_max3_f32 v77, v77, v78, v79
	v_mov_b32_e32 v78, v77
	s_nop 1
	v_permlane32_swap_b32_e32 v77, v78
	v_max_f32_e32 v78, v78, v78
	v_max_f32_e32 v77, v77, v77
	v_max_f32_e32 v77, v77, v78
	v_sub_f32_e32 v78, v77, v217
	v_cmp_gt_f32_e32 vcc, s36, v78
	s_cmp_eq_u64 vcc, exec
	s_cbranch_scc1 .LBB0_461
	v_max_f32_e32 v77, v77, v77
	v_add_f32_e32 v78, 0x41000000, v217
	v_cmp_gt_f32_e32 vcc, v77, v78
	s_nop 1
	v_cndmask_b32_e32 v135, v217, v77, vcc
	v_sub_f32_e32 v77, v217, v135
	v_exp_f32_e32 v77, v77
	s_nop 0
	v_cmp_neq_f32_e32 vcc, 1.0, v77
	s_cbranch_vccz .LBB0_459
	s_and_saveexec_b64 s[12:13], s[8:9]
	ds_write_b32 v139, v77 offset:36864
	s_or_b64 exec, exec, s[12:13]
	v_add_u32_e32 v89, s69, v0
	ds_read_b128 v[78:81], v89 offset:36960
	ds_read_b128 v[90:93], v89 offset:36928
	ds_read_b128 v[94:97], v89 offset:36896
	ds_read_b128 v[218:221], v89 offset:36864
	s_waitcnt lgkmcnt(3)
	v_pk_mul_f32 v[62:63], v[62:63], v[78:79]
	s_waitcnt lgkmcnt(2)
	v_pk_mul_f32 v[58:59], v[58:59], v[90:91]
	s_waitcnt lgkmcnt(1)
	v_pk_mul_f32 v[54:55], v[54:55], v[94:95]
	v_pk_mul_f32 v[64:65], v[64:65], v[80:81]
	v_pk_mul_f32 v[60:61], v[60:61], v[92:93]
	v_pk_mul_f32 v[56:57], v[56:57], v[96:97]
	s_waitcnt lgkmcnt(0)
	v_pk_mul_f32 v[52:53], v[52:53], v[220:221]
	v_pk_mul_f32 v[50:51], v[50:51], v[218:219]
	v_pk_mul_f32 v[46:47], v[46:47], v[78:79]
	v_pk_mul_f32 v[42:43], v[42:43], v[90:91]
	v_pk_mul_f32 v[38:39], v[38:39], v[94:95]
	v_pk_mul_f32 v[48:49], v[48:49], v[80:81]
	v_pk_mul_f32 v[44:45], v[44:45], v[92:93]
	v_pk_mul_f32 v[40:41], v[40:41], v[96:97]
	v_pk_mul_f32 v[36:37], v[36:37], v[220:221]
	v_pk_mul_f32 v[34:35], v[34:35], v[218:219]

; #define LAS __attribute__((address_space(3)))
; __device__ __forceinline__ float pair_max(float v) { float a, b; lohi(v, a, b); return fmaxf(a, b); }
; __device__ __forceinline__ void softmax_pv(f32x16& p0, f32x16& p1, float& m, float& l, f32x16 (&o)[2], LAS float* wsf, const LAS unsigned char* vp, int r32, int hi) {
;     float rm = fmaxf(p0[0], p1[0]);
; #pragma unroll
;     for (int r = 1; r < 16; ++r) rm = fmaxf(rm, fmaxf(p0[r], p1[r]));
;     rm = pair_max(rm);
;     if (__all(rm - m < -151.0f)) return;
;     const float mnew = fmaxf(m, rm), alpha = __builtin_amdgcn_exp2f(m - mnew);
;     m = mnew;
;     float s = 0.f;
; #pragma unroll
;     for (int r = 0; r < 16; ++r) { p0[r] = __builtin_amdgcn_exp2f(p0[r] - mnew); p1[r] = __builtin_amdgcn_exp2f(p1[r] - mnew); s += p0[r] + p1[r]; }
;     l = l * alpha + s;
;     if (__any(alpha != 1.0f)) {
;         if (hi == 0) wsf[r32] = alpha;
; #pragma unroll
;         for (int r = 0; r < 16; ++r) { const float f = wsf[(r & 3) + 8 * (r >> 2) + 4 * hi]; o[0][r] *= f; o[1][r] *= f; }
; template <int VAR>
; __device__ __forceinline__ void attn_unit(LAS unsigned char* lds, const AttnArgs& A, int b, int h, int qb, const int tid) {
;     ...
;                     for (int dd = 0; dd < 2; ++dd) {
;                         const int d0 = 2 * mp + dd;
;                         const bf16x8 b0 = *(const LAS bf16x8*)(kb + d0 * 2048), b1 = *(const LAS bf16x8*)(kb + d0 * 2048 + 512);
;                         p0 = __builtin_amdgcn_mfma_f32_32x32x16_bf16(b0, qr[d0], p0, 0, 0, 0);
;                         p1 = __builtin_amdgcn_mfma_f32_32x32x16_bf16(b1, qr[d0], p1, 0, 0, 0);
;                     }
;                     __builtin_amdgcn_s_setprio(0);
; #pragma unroll
;                     for (int r = 0; r < 16; ++r) {
;                         const float c0 = (float)((r & 3) + 8 * (r >> 2));
;                         p0[r] = __builtin_fmaf(-slope2, __builtin_fabsf(tb - c0), p0[r]);
;                         p1[r] = __builtin_fmaf(-slope2, __builtin_fabsf(tb - (c0 + 32.0f)), p1[r]);
;                     }
;                     if (mp == 0) softmax_pv(p0, p1, m1, l1, o, wsf, vp, r32, hi);
;                     else softmax_pv(p0, p1, m2, l2, o2, wsf, vp, r32, hi);
.LBB0_462:
	s_setprio 1
	ds_read_b128 v[66:69], v145 offset:4096
	ds_read_b128 v[82:85], v145 offset:4608
	ds_read_b128 v[206:209], v145 offset:6144
	s_waitcnt lgkmcnt(2)
	v_mfma_f32_32x32x16_bf16 v[66:81], v[66:69], v[106:109], 0
	s_waitcnt lgkmcnt(0)
	v_mfma_f32_32x32x16_bf16 v[66:81], v[206:209], v[110:113], v[66:81]
	ds_read_b128 v[206:209], v145 offset:6656
	v_mfma_f32_32x32x16_bf16 v[82:97], v[82:85], v[106:109], 0
	s_waitcnt lgkmcnt(0)
	v_mfma_f32_32x32x16_bf16 v[82:97], v[206:209], v[110:113], v[82:97]
	s_setprio 0
	s_nop 6
	v_fma_f32 v207, v138, |v147|, v67
	s_nop 2
	v_fma_f32 v206, v138, |v148|, v83
	v_fma_f32 v209, v138, |v134|, v66
	v_fma_f32 v208, v138, |v146|, v82
	v_fma_f32 v205, v138, |v149|, v68
	v_fma_f32 v193, v138, |v150|, v84
	v_fma_f32 v192, v138, |v151|, v69
	v_fma_f32 v151, v138, |v152|, v85
	v_fma_f32 v84, v138, |v178|, v75
	v_fma_f32 v75, v138, |v182|, v77
	v_max_f32_e32 v77, v207, v206
	v_fma_f32 v150, v138, |v153|, v70
	v_fma_f32 v149, v138, |v166|, v86
	v_fma_f32 v148, v138, |v167|, v71
	v_fma_f32 v147, v138, |v168|, v87
	v_fma_f32 v145, v138, |v170|, v88
	v_fma_f32 v88, v138, |v171|, v73
	v_fma_f32 v73, v138, |v184|, v78
	v_fma_f32 v71, v138, |v186|, v79
	v_max3_f32 v77, v209, v208, v77
	v_max_f32_e32 v78, v205, v193
	v_max_f32_e32 v79, v192, v151
	v_fma_f32 v146, v138, |v169|, v72
	v_fma_f32 v87, v138, |v172|, v89
	v_max3_f32 v77, v77, v78, v79
	v_max_f32_e32 v78, v150, v149
	v_max_f32_e32 v79, v148, v147
	v_fma_f32 v86, v138, |v173|, v74
	v_fma_f32 v85, v138, |v177|, v90
	v_fma_f32 v83, v138, |v179|, v91
	v_max3_f32 v77, v77, v78, v79
	v_max_f32_e32 v78, v146, v145
	v_max_f32_e32 v79, v88, v87
	v_fma_f32 v82, v138, |v180|, v76
	v_fma_f32 v76, v138, |v181|, v92
	v_fma_f32 v74, v138, |v183|, v93
	v_max3_f32 v77, v77, v78, v79
	v_max_f32_e32 v78, v86, v85
	v_max_f32_e32 v79, v84, v83
	v_fma_f32 v72, v138, |v185|, v94
	v_fma_f32 v70, v138, |v187|, v95
	v_max3_f32 v77, v77, v78, v79
	v_max_f32_e32 v78, v82, v76
	v_max_f32_e32 v79, v75, v74
	v_fma_f32 v69, v138, |v188|, v80
	v_fma_f32 v68, v138, |v189|, v96
	v_fma_f32 v67, v138, |v190|, v81
	v_fma_f32 v66, v138, |v191|, v97
	v_max3_f32 v77, v77, v78, v79
	v_max_f32_e32 v78, v73, v72
	v_max_f32_e32 v79, v71, v70
	v_max3_f32 v77, v77, v78, v79
	v_max_f32_e32 v78, v69, v68
	v_max_f32_e32 v79, v67, v66
	v_max3_f32 v77, v77, v78, v79
	v_mov_b32_e32 v78, v77
	s_nop 1
	v_permlane32_swap_b32_e32 v77, v78
	v_max_f32_e32 v78, v78, v78
	v_max_f32_e32 v77, v77, v77
	v_max_f32_e32 v77, v77, v78
	v_sub_f32_e32 v78, v77, v144
	v_cmp_gt_f32_e32 vcc, s36, v78
	s_cmp_eq_u64 vcc, exec
	s_cbranch_scc1 .LBB0_468
	v_max_f32_e32 v77, v77, v77
	v_add_f32_e32 v78, 0x41000000, v144
	v_cmp_gt_f32_e32 vcc, v77, v78
	s_nop 1
	v_cndmask_b32_e32 v134, v144, v77, vcc
	v_sub_f32_e32 v77, v144, v134
	v_exp_f32_e32 v77, v77
	s_nop 0
	v_cmp_neq_f32_e32 vcc, 1.0, v77
	s_cbranch_vccz .LBB0_467
	s_and_saveexec_b64 s[12:13], s[8:9]
	ds_write_b32 v139, v77 offset:36864
	s_or_b64 exec, exec, s[12:13]
	v_add_u32_e32 v89, s69, v0
	ds_read_b128 v[78:81], v89 offset:36960
	ds_read_b128 v[90:93], v89 offset:36928
	ds_read_b128 v[94:97], v89 offset:36896
	ds_read_b128 v[166:169], v89 offset:36864
	s_waitcnt lgkmcnt(3)
	v_pk_mul_f32 v[30:31], v[30:31], v[78:79]
	s_waitcnt lgkmcnt(2)
	v_pk_mul_f32 v[26:27], v[26:27], v[90:91]
	s_waitcnt lgkmcnt(1)
	v_pk_mul_f32 v[22:23], v[22:23], v[94:95]
	v_pk_mul_f32 v[32:33], v[32:33], v[80:81]
	v_pk_mul_f32 v[28:29], v[28:29], v[92:93]
	v_pk_mul_f32 v[24:25], v[24:25], v[96:97]
	s_waitcnt lgkmcnt(0)
	v_pk_mul_f32 v[20:21], v[20:21], v[168:169]
	v_pk_mul_f32 v[18:19], v[18:19], v[166:167]
	v_pk_mul_f32 v[14:15], v[14:15], v[78:79]
	v_pk_mul_f32 v[10:11], v[10:11], v[90:91]
	v_pk_mul_f32 v[6:7], v[6:7], v[94:95]
	v_pk_mul_f32 v[16:17], v[16:17], v[80:81]
	v_pk_mul_f32 v[12:13], v[12:13], v[92:93]
	v_pk_mul_f32 v[8:9], v[8:9], v[96:97]
	v_pk_mul_f32 v[4:5], v[4:5], v[168:169]
	v_pk_mul_f32 v[2:3], v[2:3], v[166:167]

; __device__ __forceinline__ void softmax_pv(f32x16& p0, f32x16& p1, float& m, float& l, f32x16 (&o)[2], LAS float* wsf, const LAS unsigned char* vp, int r32, int hi) {
;     float rm = fmaxf(p0[0], p1[0]);
; #pragma unroll
;     for (int r = 1; r < 16; ++r) rm = fmaxf(rm, fmaxf(p0[r], p1[r]));
;     rm = pair_max(rm);
;     if (__all(rm - m < -151.0f)) return;
; template <int VAR>
; __device__ __forceinline__ void attn_unit(LAS unsigned char* lds, const AttnArgs& A, int b, int h, int qb, const int tid) {
;     ...
;                 f32x16 p0, p1;
; #pragma unroll
;                 for (int r = 0; r < 16; ++r) { p0[r] = 0.f; p1[r] = 0.f; }
;                 __builtin_amdgcn_s_setprio(1);
; #pragma unroll
;                 for (int d0 = 0; d0 < 4; ++d0) {
;                     const bf16x8 b0 = *(const LAS bf16x8*)(kb + d0 * 2048), b1 = *(const LAS bf16x8*)(kb + d0 * 2048 + 512);
;                     p0 = __builtin_amdgcn_mfma_f32_32x32x16_bf16(b0, qr[d0], p0, 0, 0, 0);
;                     p1 = __builtin_amdgcn_mfma_f32_32x32x16_bf16(b1, qr[d0], p1, 0, 0, 0);
;                 }
;                 __builtin_amdgcn_s_setprio(0);
;                 if (VAR == 0) {
;                     const LAS float* fs = FS + buf * 64 + 4 * hi;
; #pragma unroll
;                     for (int a = 0; a < 4; ++a) {
;                         const f32x4 f0 = *(const LAS f32x4*)(fs + 8 * a), f1 = *(const LAS f32x4*)(fs + 32 + 8 * a);
; #pragma unroll
;                         for (int j = 0; j < 4; ++j) { p0[4 * a + j] += Ft - f0[j]; p1[4 * a + j] += Ft - f1[j]; }
;                     }
;                     if (diag) {
;                         const float tlf = (float)tl;
; #pragma unroll
;                         for (int r = 0; r < 16; ++r) { const float c0 = (float)((r & 3) + 8 * (r >> 2));
;                             p0[r] = __builtin_fmaf(fminf(tlf - c0, 0.f), 1e30f, p0[r]); p1[r] = __builtin_fmaf(fminf(tlf - (c0 + 32.0f), 0.f), 1e30f, p1[r]); }
;                     }
;                     softmax_pv(p0, p1, m1, l1, o, wsf, vp, r32, hi);
;                     wdone = __all(qkb1 + (Ft - FS[buf * 64]) - m1 < -151.0f);
;                 } else if (VAR == 1) {
;                     const LAS float* eb = EXTL + (576 - tl);
; #pragma unroll
;                     for (int r = 0; r < 16; ++r) { const int c0 = (r & 3) + 8 * (r >> 2); p0[r] += eb[c0]; p1[r] += eb[c0 + 32]; }
.LBB0_489:
	s_add_i32 s38, s71, 2
	s_cmp_gt_i32 s38, s11
	s_cselect_b64 s[12:13], -1, 0
	s_cmp_lt_i32 s38, s28
	s_cselect_b64 s[38:39], -1, 0
	s_or_b64 s[12:13], s[12:13], s[38:39]
	s_and_b64 vcc, exec, s[12:13]
	s_cbranch_vccnz .LBB0_496
	s_add_i32 s12, s81, 0xffffe000
	s_and_b32 s50, s12, 0x2000
	v_add_u32_e32 v108, s50, v97
	s_setprio 1
	ds_read_b128 v[126:129], v108
	ds_read_b128 v[130:133], v108 offset:2048
	ds_read_b128 v[134:137], v108 offset:512
	ds_read_b128 v[138:141], v108 offset:2560
	ds_read_b128 v[146:149], v108 offset:4096
	ds_read_b128 v[150:153], v108 offset:4608
	ds_read_b128 v[166:169], v108 offset:6144
	ds_read_b128 v[170:173], v108 offset:6656
	s_waitcnt lgkmcnt(7)
	v_mfma_f32_32x32x16_bf16 v[34:49], v[126:129], v[66:69], 0
	s_waitcnt lgkmcnt(6)
	v_mfma_f32_32x32x16_bf16 v[34:49], v[130:133], v[70:73], v[34:49]
	s_waitcnt lgkmcnt(5)
	v_mfma_f32_32x32x16_bf16 v[50:65], v[134:137], v[66:69], 0
	s_waitcnt lgkmcnt(4)
	v_mfma_f32_32x32x16_bf16 v[50:65], v[138:141], v[70:73], v[50:65]
	s_waitcnt lgkmcnt(3)
	v_mfma_f32_32x32x16_bf16 v[34:49], v[146:149], v[74:77], v[34:49]
	s_waitcnt lgkmcnt(2)
	v_mfma_f32_32x32x16_bf16 v[50:65], v[150:153], v[74:77], v[50:65]
	s_waitcnt lgkmcnt(1)
	v_mfma_f32_32x32x16_bf16 v[34:49], v[166:169], v[78:81], v[34:49]
	s_waitcnt lgkmcnt(0)
	v_mfma_f32_32x32x16_bf16 v[50:65], v[170:173], v[78:81], v[50:65]
	s_setprio 0
	ds_read2_b32 v[206:207], v101 offset1:1
	ds_read2_b32 v[208:209], v101 offset0:32 offset1:33
	ds_read2_b32 v[210:211], v101 offset0:34 offset1:35
	ds_read2_b32 v[212:213], v101 offset0:2 offset1:3
	ds_read2_b32 v[214:215], v101 offset0:8 offset1:9
	ds_read2_b32 v[216:217], v101 offset0:40 offset1:41
	ds_read2_b32 v[218:219], v101 offset0:10 offset1:11
	ds_read2_b32 v[220:221], v101 offset0:42 offset1:43
	ds_read2_b32 v[222:223], v101 offset0:16 offset1:17
	ds_read2_b32 v[224:225], v101 offset0:48 offset1:49
	ds_read2_b32 v[226:227], v101 offset0:18 offset1:19
	ds_read2_b32 v[228:229], v101 offset0:50 offset1:51
	ds_read2_b32 v[230:231], v101 offset0:24 offset1:25
	ds_read2_b32 v[232:233], v101 offset0:56 offset1:57
	ds_read2_b32 v[234:235], v101 offset0:26 offset1:27
	ds_read2_b32 v[236:237], v101 offset0:58 offset1:59
	s_waitcnt lgkmcnt(15)
	v_add_f32_e32 v34, v34, v206
	s_waitcnt lgkmcnt(14)
	v_add_f32_e32 v104, v50, v208
	v_add_f32_e32 v50, v35, v207
	v_add_f32_e32 v35, v51, v209
	s_waitcnt lgkmcnt(13)
	v_add_f32_e32 v52, v52, v210
	s_waitcnt lgkmcnt(12)
	v_add_f32_e32 v51, v36, v212
	v_add_f32_e32 v37, v37, v213
	v_add_f32_e32 v36, v53, v211
	s_waitcnt lgkmcnt(11)
	v_add_f32_e32 v105, v38, v214
	s_waitcnt lgkmcnt(10)
	v_add_f32_e32 v54, v54, v216
	v_add_f32_e32 v53, v39, v215
	v_add_f32_e32 v39, v55, v217
	v_max_f32_e32 v38, v50, v35
	v_max3_f32 v38, v34, v104, v38
	s_waitcnt lgkmcnt(9)
	v_add_f32_e32 v40, v40, v218
	s_waitcnt lgkmcnt(8)
	v_add_f32_e32 v56, v56, v220
	v_add_f32_e32 v55, v41, v219
	v_add_f32_e32 v41, v57, v221
	s_waitcnt lgkmcnt(7)
	v_add_f32_e32 v42, v42, v222
	s_waitcnt lgkmcnt(6)
	v_add_f32_e32 v58, v58, v224
	v_add_f32_e32 v57, v43, v223
	v_add_f32_e32 v43, v59, v225
	s_waitcnt lgkmcnt(5)
	v_add_f32_e32 v59, v44, v226
	s_waitcnt lgkmcnt(4)
	v_add_f32_e32 v60, v60, v228
	v_add_f32_e32 v45, v45, v227
	v_add_f32_e32 v44, v61, v229
	s_waitcnt lgkmcnt(3)
	v_add_f32_e32 v61, v46, v230
	s_waitcnt lgkmcnt(2)
	v_add_f32_e32 v62, v62, v232
	v_add_f32_e32 v47, v47, v231
	v_add_f32_e32 v46, v63, v233
	s_waitcnt lgkmcnt(1)
	v_add_f32_e32 v48, v48, v234
	v_add_f32_e32 v63, v49, v235
	s_waitcnt lgkmcnt(0)
	v_add_u32_e32 v194, s50, v99
	ds_read_b64_tr_b16 v[238:239], v194 offset:16384
	ds_read_b64_tr_b16 v[240:241], v194 offset:16896
	ds_read_b64_tr_b16 v[242:243], v194 offset:17408
	ds_read_b64_tr_b16 v[244:245], v194 offset:17920
	ds_read_b64_tr_b16 v[246:247], v194 offset:18432
	ds_read_b64_tr_b16 v[248:249], v194 offset:18944
	ds_read_b64_tr_b16 v[250:251], v194 offset:19456
	ds_read_b64_tr_b16 v[252:253], v194 offset:19968
	ds_read_b64_tr_b16 v[178:179], v194 offset:20480
	ds_read_b64_tr_b16 v[180:181], v194 offset:20992
	ds_read_b64_tr_b16 v[182:183], v194 offset:21504
	ds_read_b64_tr_b16 v[184:185], v194 offset:22016
	ds_read_b64_tr_b16 v[186:187], v194 offset:22528
	ds_read_b64_tr_b16 v[188:189], v194 offset:23040
	ds_read_b64_tr_b16 v[190:191], v194 offset:23552
	ds_read_b64_tr_b16 v[192:193], v194 offset:24064
	v_add_f32_e32 v49, v65, v237
	v_max_f32_e32 v65, v51, v52
	v_max_f32_e32 v106, v37, v36
	v_max3_f32 v38, v38, v65, v106
	v_max_f32_e32 v65, v105, v54
	v_max_f32_e32 v106, v53, v39
	v_max3_f32 v38, v38, v65, v106
	v_max_f32_e32 v65, v40, v56
	v_max_f32_e32 v106, v55, v41
	v_max3_f32 v38, v38, v65, v106
	v_max_f32_e32 v65, v42, v58
	v_max_f32_e32 v106, v57, v43
	v_max3_f32 v38, v38, v65, v106
	v_max_f32_e32 v65, v59, v60
	v_max_f32_e32 v106, v45, v44
	v_add_f32_e32 v64, v64, v236
	v_max3_f32 v38, v38, v65, v106
	v_max_f32_e32 v65, v61, v62
	v_max_f32_e32 v106, v47, v46
	v_max3_f32 v38, v38, v65, v106
	v_max_f32_e32 v65, v48, v64
	v_max_f32_e32 v106, v63, v49
	v_max3_f32 v38, v38, v65, v106
	v_mov_b32_e32 v65, v38
	s_nop 1
	v_permlane32_swap_b32_e32 v38, v65
	v_max_f32_e32 v65, v65, v65
	v_max_f32_e32 v38, v38, v38
	v_max_f32_e32 v38, v38, v65
	v_sub_f32_e32 v65, v38, v103
	v_cmp_gt_f32_e32 vcc, s36, v65
	s_cmp_eq_u64 vcc, exec
	s_cbranch_scc1 .LBB0_496
	v_max_f32_e32 v38, v38, v38
	v_add_f32_e32 v65, 0x41000000, v103
	v_cmp_gt_f32_e32 vcc, v38, v65
	s_nop 1
	v_cndmask_b32_e32 v38, v103, v38, vcc
	v_sub_f32_e32 v65, v103, v38
	v_exp_f32_e32 v65, v65
	s_nop 0
	v_cmp_neq_f32_e32 vcc, 1.0, v65
	s_cbranch_vccz .LBB0_495
	s_and_saveexec_b64 s[12:13], s[8:9]
	ds_write_b32 v100, v65 offset:36864
	s_or_b64 exec, exec, s[12:13]
	v_add_u32_e32 v103, s68, v0
	ds_read_b128 v[106:109], v103 offset:36960
	ds_read_b128 v[110:113], v103 offset:36928
	ds_read_b128 v[114:117], v103 offset:36896
	ds_read_b128 v[118:121], v103 offset:36864
	s_waitcnt lgkmcnt(3)
	v_pk_mul_f32 v[30:31], v[30:31], v[106:107]
	s_waitcnt lgkmcnt(2)
	v_pk_mul_f32 v[26:27], v[26:27], v[110:111]
	s_waitcnt lgkmcnt(1)
	v_pk_mul_f32 v[22:23], v[22:23], v[114:115]
	s_waitcnt lgkmcnt(0)
	v_pk_mul_f32 v[18:19], v[18:19], v[118:119]
	v_pk_mul_f32 v[14:15], v[14:15], v[106:107]
	v_pk_mul_f32 v[10:11], v[10:11], v[110:111]
	v_pk_mul_f32 v[6:7], v[6:7], v[114:115]
	v_pk_mul_f32 v[32:33], v[32:33], v[108:109]
	v_pk_mul_f32 v[28:29], v[28:29], v[112:113]
	v_pk_mul_f32 v[24:25], v[24:25], v[116:117]
	v_pk_mul_f32 v[20:21], v[20:21], v[120:121]
	v_pk_mul_f32 v[16:17], v[16:17], v[108:109]
	v_pk_mul_f32 v[12:13], v[12:13], v[112:113]
	v_pk_mul_f32 v[8:9], v[8:9], v[116:117]
	v_pk_mul_f32 v[4:5], v[4:5], v[120:121]
	v_pk_mul_f32 v[2:3], v[2:3], v[118:119]

; __device__ __forceinline__ float pair_max(float v) { float a, b; lohi(v, a, b); return fmaxf(a, b); }
; __device__ __forceinline__ void softmax_pv(f32x16& p0, f32x16& p1, float& m, float& l, f32x16 (&o)[2], LAS float* wsf, const LAS unsigned char* vp, int r32, int hi) {
;     float rm = fmaxf(p0[0], p1[0]);
; #pragma unroll
;     for (int r = 1; r < 16; ++r) rm = fmaxf(rm, fmaxf(p0[r], p1[r]));
;     rm = pair_max(rm);
;     if (__all(rm - m < -151.0f)) return;
;     const float mnew = fmaxf(m, rm), alpha = __builtin_amdgcn_exp2f(m - mnew);
;     m = mnew;
;     float s = 0.f;
; #pragma unroll
;     for (int r = 0; r < 16; ++r) { p0[r] = __builtin_amdgcn_exp2f(p0[r] - mnew); p1[r] = __builtin_amdgcn_exp2f(p1[r] - mnew); s += p0[r] + p1[r]; }
;     l = l * alpha + s;
;     if (__any(alpha != 1.0f)) {
;         if (hi == 0) wsf[r32] = alpha;
; #pragma unroll
;         for (int r = 0; r < 16; ++r) { const float f = wsf[(r & 3) + 8 * (r >> 2) + 4 * hi]; o[0][r] *= f; o[1][r] *= f; }
.LBB0_522:
	s_nop 0
	v_max_f32_e32 v64, v51, v51
	v_max_f32_e32 v65, v137, v137
	v_max_f32_e32 v64, v65, v64
	v_max_f32_e32 v65, v36, v36
	v_max_f32_e32 v147, v34, v34
	v_max_f32_e32 v65, v147, v65
	v_max_f32_e32 v147, v37, v37
	v_max_f32_e32 v148, v35, v35
	v_max3_f32 v64, v136, v50, v64
	v_max_f32_e32 v147, v148, v147
	v_max3_f32 v64, v64, v65, v147
	v_max_f32_e32 v65, v54, v54
	v_max_f32_e32 v147, v52, v52
	v_max_f32_e32 v65, v147, v65
	v_max_f32_e32 v147, v55, v55
	v_max_f32_e32 v148, v53, v53
	v_max_f32_e32 v147, v148, v147
	v_max3_f32 v64, v64, v65, v147
	v_max_f32_e32 v65, v40, v40
	v_max_f32_e32 v147, v38, v38
	v_max_f32_e32 v65, v147, v65
	v_max_f32_e32 v147, v41, v41
	v_max_f32_e32 v148, v39, v39
	v_max_f32_e32 v147, v148, v147
	v_max3_f32 v64, v64, v65, v147
	v_max_f32_e32 v65, v58, v58
	v_max_f32_e32 v147, v56, v56
	v_max_f32_e32 v65, v147, v65
	v_max_f32_e32 v147, v59, v59
	v_max_f32_e32 v148, v57, v57
	v_max_f32_e32 v147, v148, v147
	v_max3_f32 v64, v64, v65, v147
	v_max_f32_e32 v65, v44, v44
	v_max_f32_e32 v147, v42, v42
	v_max_f32_e32 v65, v147, v65
	v_max_f32_e32 v147, v45, v45
	v_max_f32_e32 v148, v43, v43
	v_max_f32_e32 v147, v148, v147
	v_max3_f32 v64, v64, v65, v147
	v_max_f32_e32 v65, v62, v62
	v_max_f32_e32 v147, v60, v60
	v_max_f32_e32 v65, v147, v65
	v_max_f32_e32 v147, v63, v63
	v_max_f32_e32 v148, v61, v61
	v_max_f32_e32 v147, v148, v147
	v_max3_f32 v64, v64, v65, v147
	v_max_f32_e32 v65, v48, v48
	v_max_f32_e32 v147, v46, v46
	v_max_f32_e32 v65, v147, v65
	v_max_f32_e32 v147, v49, v49
	v_max_f32_e32 v148, v47, v47
	v_max_f32_e32 v147, v148, v147
	v_max3_f32 v64, v64, v65, v147
	v_mov_b32_e32 v65, v64
	s_nop 1
	v_permlane32_swap_b32_e32 v64, v65
	v_max_f32_e32 v65, v65, v65
	v_max_f32_e32 v64, v64, v64
	v_max_f32_e32 v64, v64, v65
	v_sub_f32_e32 v65, v64, v146
	v_cmp_gt_f32_e32 vcc, s36, v65
	s_cmp_eq_u64 vcc, exec
	s_cbranch_scc1 .LBB0_533
	v_max_f32_e32 v64, v64, v64
	v_add_f32_e32 v65, 0x41000000, v146
	v_cmp_gt_f32_e32 vcc, v64, v65
	s_nop 1
	v_cndmask_b32_e32 v64, v146, v64, vcc
	v_sub_f32_e32 v65, v146, v64
	v_exp_f32_e32 v65, v65
	s_nop 0
	v_cmp_neq_f32_e32 vcc, 1.0, v65
	s_cbranch_vccz .LBB0_527
	s_and_saveexec_b64 s[70:71], s[10:11]
	ds_write_b32 v144, v65 offset:36864
	s_or_b64 exec, exec, s[70:71]
	ds_read_b128 v[146:149], v0 offset:36960
	ds_read_b128 v[150:153], v0 offset:36928
	ds_read_b128 v[166:169], v0 offset:36896
	ds_read_b128 v[170:173], v0 offset:36864
	s_waitcnt lgkmcnt(3)
	v_pk_mul_f32 v[30:31], v[30:31], v[146:147]
	s_waitcnt lgkmcnt(2)
	v_pk_mul_f32 v[26:27], v[26:27], v[150:151]
	s_waitcnt lgkmcnt(1)
	v_pk_mul_f32 v[22:23], v[22:23], v[166:167]
	v_pk_mul_f32 v[32:33], v[32:33], v[148:149]
	v_pk_mul_f32 v[28:29], v[28:29], v[152:153]
	v_pk_mul_f32 v[24:25], v[24:25], v[168:169]
	s_waitcnt lgkmcnt(0)
	v_pk_mul_f32 v[20:21], v[20:21], v[172:173]
	v_pk_mul_f32 v[18:19], v[18:19], v[170:171]
	v_pk_mul_f32 v[14:15], v[14:15], v[146:147]
	v_pk_mul_f32 v[10:11], v[10:11], v[150:151]
	v_pk_mul_f32 v[6:7], v[6:7], v[166:167]
	v_pk_mul_f32 v[16:17], v[16:17], v[148:149]
	v_pk_mul_f32 v[12:13], v[12:13], v[152:153]
	v_pk_mul_f32 v[8:9], v[8:9], v[168:169]
	v_pk_mul_f32 v[4:5], v[4:5], v[172:173]
	v_pk_mul_f32 v[2:3], v[2:3], v[170:171]
